# v51: prep rebalance after the cpe move - workgroups 0..63 now sit out only the last weight-conversion iteration (they had ~30 us slack)
# baseline (speedup 1.0000x reference)
.LBB0_20:
	v_readlane_b32 s0, v254, 1
	v_readlane_b32 s33, v254, 0
	v_readlane_b32 s1, v254, 2
	s_load_dword s0, s[0:1], 0x10
	v_readlane_b32 s36, v254, 19
	s_mul_i32 s2, s8, 0x3000
	v_readlane_b32 s38, v254, 21
	v_readlane_b32 s39, v254, 22
	s_waitcnt lgkmcnt(0)
	s_lshr_b32 s0, s0, 16
	s_cmp_lg_u32 s0, 0
	s_cselect_b64 s[0:1], -1, 0
	s_cmp_lg_u64 s[0:1], 0
	s_addc_u32 s18, s69, 0
	s_lshl_b32 s26, s8, 1
	s_add_u32 s70, s38, s2
	s_addc_u32 s71, s39, 0
	s_mul_i32 s0, s8, 0x2100000
	v_readlane_b32 s2, v254, 40
	s_mul_hi_u32 s1, s26, 0x1080000
	v_readlane_b32 s3, v254, 41
	s_add_u32 s0, s2, s0
	s_addc_u32 s1, s3, s1
	s_mov_b32 s27, s18
	s_cmp_eq_u32 s18, 0x100
	s_cbranch_scc0 .Lw_norm
	s_cmp_ge_u32 s8, 3
	s_cbranch_scc0 .Lw_norm
	s_cmp_lt_u32 s33, 64
	s_cbranch_scc1 .LBB0_19
	s_sub_i32 s33, s33, 64
	s_movk_i32 s27, 0xc0

.LBB0_401:
	s_or_b32 s26, s26, 1
	s_add_u32 s24, s70, 0x2000
	s_addc_u32 s25, s71, 0
	s_mul_i32 s0, s26, 0x1080000
	v_readlane_b32 s2, v254, 40
	s_mul_hi_u32 s1, s26, 0x1080000
	v_readlane_b32 s3, v254, 41
	s_add_u32 s0, s2, s0
	v_readlane_b32 s12, v254, 0
	s_addc_u32 s1, s3, s1
	s_mov_b32 s13, s18
	s_cmp_eq_u32 s18, 0x100
	s_cbranch_scc0 .Lw_norm2
	s_cmp_ge_u32 s8, 3
	s_cbranch_scc0 .Lw_norm2
	s_sub_i32 s12, s12, 64
	s_movk_i32 s13, 0xc0
